# initial x->bf16 phase: 8 chunk loads of a row in flight together and next row prefetched before the row-end reduction (was one load in flight with a full wait per chunk)
# baseline (speedup 1.0000x reference)
; __device__ __forceinline__ unsigned pk_bf16(float lo, float hi) { return pg8::cvt_pk_bf16(lo, hi); }
; __device__ __forceinline__ void xinit_phase(const float* xin, bf16_t* xb, unsigned long long* ss) {
;     ...
;     for (int row = gw; row < MTOK; row += NGW) {
;         const f32x4* xr = (const f32x4*)(xin + (size_t)row * DM) + lane;
;         u32x2* o = (u32x2*)(xb + (size_t)row * DM) + lane;
;         float s = 0.f;
; #pragma unroll
;         for (int j = 0; j < 8; ++j) { const f32x4 v = xr[64 * j]; u32x2 w; w.x = pk_bf16(v.x, v.y); w.y = pk_bf16(v.z, v.w); o[64 * j] = w;
.Lxh_first:
	global_load_dwordx4 v[36:39], v[4:5], off offset:-4096
	global_load_dwordx4 v[40:43], v[4:5], off offset:-3072
	global_load_dwordx4 v[44:47], v[4:5], off offset:-2048
	global_load_dwordx4 v[48:51], v[4:5], off offset:-1024
	global_load_dwordx4 v[52:55], v[4:5], off
	global_load_dwordx4 v[56:59], v[4:5], off offset:1024
	global_load_dwordx4 v[60:63], v[4:5], off offset:2048
	global_load_dwordx4 v[64:67], v[4:5], off offset:3072
	s_branch .LBB0_26

; __device__ __forceinline__ unsigned pk_bf16(float lo, float hi) { return pg8::cvt_pk_bf16(lo, hi); }
; __device__ __forceinline__ float bf_lo(unsigned w) { return __uint_as_float(w << 16); }
; __device__ __forceinline__ float bf_hi(unsigned w) { return __uint_as_float(w & 0xffff0000u); }
; __device__ __forceinline__ void xinit_phase(const float* xin, bf16_t* xb, unsigned long long* ss) {
;     ...
;     for (int row = gw; row < MTOK; row += NGW) {
;         const f32x4* xr = (const f32x4*)(xin + (size_t)row * DM) + lane;
;         u32x2* o = (u32x2*)(xb + (size_t)row * DM) + lane;
;         float s = 0.f;
; #pragma unroll
;         for (int j = 0; j < 8; ++j) { const f32x4 v = xr[64 * j]; u32x2 w; w.x = pk_bf16(v.x, v.y); w.y = pk_bf16(v.z, v.w); o[64 * j] = w;
;             const float a = bf_lo(w.x), b = bf_hi(w.x), c = bf_lo(w.y), d = bf_hi(w.y); s += (a * a + b * b) + (c * c + d * d); }
;         s = wave_sum(s);
;         if (lane == 0) ss[row] = (unsigned long long)(s * 16777216.f);
;     }
.LBB0_26:
	s_waitcnt lgkmcnt(0)
	v_lshl_add_u64 v[18:19], s[6:7], 0, v[6:7]
	v_add_co_u32_e32 v18, vcc, 0x15c00000, v18
	s_nop 1
	v_addc_co_u32_e32 v19, vcc, 0, v19, vcc
	s_waitcnt vmcnt(7)
	v_cvt_pk_bf16_f32 v20, v36, v37
	v_cvt_pk_bf16_f32 v21, v38, v39
	global_store_dwordx2 v[18:19], v[20:21], off
	v_lshlrev_b32_e32 v14, 16, v20
	v_and_b32_e32 v15, 0xffff0000, v20
	v_lshlrev_b32_e32 v16, 16, v21
	v_and_b32_e32 v17, 0xffff0000, v21
	v_mul_f32_e32 v15, v15, v15
	v_mul_f32_e32 v17, v17, v17
	v_fmac_f32_e32 v15, v14, v14
	v_fmac_f32_e32 v17, v16, v16
	v_add_f32_e32 v2, v15, v17
	s_waitcnt vmcnt(7)
	v_cvt_pk_bf16_f32 v22, v40, v41
	v_cvt_pk_bf16_f32 v23, v42, v43
	global_store_dwordx2 v[18:19], v[22:23], off offset:512
	v_lshlrev_b32_e32 v14, 16, v22
	v_and_b32_e32 v15, 0xffff0000, v22
	v_lshlrev_b32_e32 v16, 16, v23
	v_and_b32_e32 v17, 0xffff0000, v23
	v_mul_f32_e32 v15, v15, v15
	v_mul_f32_e32 v17, v17, v17
	v_fmac_f32_e32 v15, v14, v14
	v_fmac_f32_e32 v17, v16, v16
	v_add_f32_e32 v14, v15, v17
	v_add_f32_e32 v2, v2, v14
	s_waitcnt vmcnt(7)
	v_cvt_pk_bf16_f32 v24, v44, v45
	v_cvt_pk_bf16_f32 v25, v46, v47
	global_store_dwordx2 v[18:19], v[24:25], off offset:1024
	v_lshlrev_b32_e32 v14, 16, v24
	v_and_b32_e32 v15, 0xffff0000, v24
	v_lshlrev_b32_e32 v16, 16, v25
	v_and_b32_e32 v17, 0xffff0000, v25
	v_mul_f32_e32 v15, v15, v15
	v_mul_f32_e32 v17, v17, v17
	v_fmac_f32_e32 v15, v14, v14
	v_fmac_f32_e32 v17, v16, v16
	v_add_f32_e32 v14, v15, v17
	v_add_f32_e32 v2, v2, v14
	s_waitcnt vmcnt(7)
	v_cvt_pk_bf16_f32 v26, v48, v49
	v_cvt_pk_bf16_f32 v27, v50, v51
	global_store_dwordx2 v[18:19], v[26:27], off offset:1536
	v_lshlrev_b32_e32 v14, 16, v26
	v_and_b32_e32 v15, 0xffff0000, v26
	v_lshlrev_b32_e32 v16, 16, v27
	v_and_b32_e32 v17, 0xffff0000, v27
	v_mul_f32_e32 v15, v15, v15
	v_mul_f32_e32 v17, v17, v17
	v_fmac_f32_e32 v15, v14, v14
	v_fmac_f32_e32 v17, v16, v16
	v_add_f32_e32 v14, v15, v17
	v_add_f32_e32 v2, v2, v14
	s_waitcnt vmcnt(7)
	v_cvt_pk_bf16_f32 v28, v52, v53
	v_cvt_pk_bf16_f32 v29, v54, v55
	global_store_dwordx2 v[18:19], v[28:29], off offset:2048
	v_lshlrev_b32_e32 v14, 16, v28
	v_and_b32_e32 v15, 0xffff0000, v28
	v_lshlrev_b32_e32 v16, 16, v29
	v_and_b32_e32 v17, 0xffff0000, v29
	v_mul_f32_e32 v15, v15, v15
	v_mul_f32_e32 v17, v17, v17
	v_fmac_f32_e32 v15, v14, v14
	v_fmac_f32_e32 v17, v16, v16
	v_add_f32_e32 v14, v15, v17
	v_add_f32_e32 v2, v2, v14
	s_waitcnt vmcnt(7)
	v_cvt_pk_bf16_f32 v30, v56, v57
	v_cvt_pk_bf16_f32 v31, v58, v59
	global_store_dwordx2 v[18:19], v[30:31], off offset:2560
	v_lshlrev_b32_e32 v14, 16, v30
	v_and_b32_e32 v15, 0xffff0000, v30
	v_lshlrev_b32_e32 v16, 16, v31
	v_and_b32_e32 v17, 0xffff0000, v31
	v_mul_f32_e32 v15, v15, v15
	v_mul_f32_e32 v17, v17, v17
	v_fmac_f32_e32 v15, v14, v14
	v_fmac_f32_e32 v17, v16, v16
	v_add_f32_e32 v14, v15, v17
	v_add_f32_e32 v2, v2, v14
	s_waitcnt vmcnt(7)
	v_cvt_pk_bf16_f32 v32, v60, v61
	v_cvt_pk_bf16_f32 v33, v62, v63
	global_store_dwordx2 v[18:19], v[32:33], off offset:3072
	v_lshlrev_b32_e32 v14, 16, v32
	v_and_b32_e32 v15, 0xffff0000, v32
	v_lshlrev_b32_e32 v16, 16, v33
	v_and_b32_e32 v17, 0xffff0000, v33
	v_mul_f32_e32 v15, v15, v15
	v_mul_f32_e32 v17, v17, v17
	v_fmac_f32_e32 v15, v14, v14
	v_fmac_f32_e32 v17, v16, v16
	v_add_f32_e32 v14, v15, v17
	v_add_f32_e32 v2, v2, v14
	s_waitcnt vmcnt(7)
	v_cvt_pk_bf16_f32 v20, v64, v65
	v_cvt_pk_bf16_f32 v21, v66, v67
	global_store_dwordx2 v[18:19], v[20:21], off offset:3584
	v_lshlrev_b32_e32 v14, 16, v20
	v_and_b32_e32 v15, 0xffff0000, v20
	v_lshlrev_b32_e32 v16, 16, v21
	v_and_b32_e32 v17, 0xffff0000, v21
	v_mul_f32_e32 v15, v15, v15
	v_mul_f32_e32 v17, v17, v17
	v_fmac_f32_e32 v15, v14, v14
	v_fmac_f32_e32 v17, v16, v16
	v_add_f32_e32 v14, v15, v17
	v_add_f32_e32 v2, v2, v14
	s_add_i32 s32, s12, s38
	s_cmpk_lt_i32 s32, 0x4000
	s_cbranch_scc0 .Lxh_nopf
	v_lshl_add_u64 v[68:69], v[4:5], 0, s[20:21]
	global_load_dwordx4 v[36:39], v[68:69], off offset:-4096
	global_load_dwordx4 v[40:43], v[68:69], off offset:-3072
	global_load_dwordx4 v[44:47], v[68:69], off offset:-2048
	global_load_dwordx4 v[48:51], v[68:69], off offset:-1024
	global_load_dwordx4 v[52:55], v[68:69], off
	global_load_dwordx4 v[56:59], v[68:69], off offset:1024
	global_load_dwordx4 v[60:63], v[68:69], off offset:2048
	global_load_dwordx4 v[64:67], v[68:69], off offset:3072
.Lxh_nopf:
	ds_bpermute_b32 v14, v8, v2
	s_waitcnt lgkmcnt(0)
	v_add_f32_e32 v2, v2, v14
	ds_bpermute_b32 v14, v9, v2
	s_waitcnt lgkmcnt(0)
	v_add_f32_e32 v2, v2, v14
	ds_bpermute_b32 v14, v10, v2
	s_waitcnt lgkmcnt(0)
	v_add_f32_e32 v2, v2, v14
	ds_bpermute_b32 v14, v11, v2
	s_waitcnt lgkmcnt(0)
	v_add_f32_e32 v2, v2, v14
	ds_bpermute_b32 v14, v12, v2
	s_waitcnt lgkmcnt(0)
	v_add_f32_e32 v2, v2, v14
	ds_bpermute_b32 v14, v13, v2
	s_and_saveexec_b64 s[24:25], s[4:5]
	s_cbranch_execz .LBB0_25
	s_waitcnt lgkmcnt(0)
	v_add_f32_e32 v2, v2, v14
	v_mul_f32_e32 v2, 0x4b800000, v2
	v_trunc_f32_e32 v2, v2
	v_mul_f32_e32 v14, 0x2f800000, v2
	v_floor_f32_e32 v15, v14
	v_fmac_f32_e32 v2, 0xcf800000, v15
	v_cvt_u32_f32_e32 v14, v2
	v_cvt_u32_f32_e32 v15, v15
	s_add_u32 s0, s6, s3
	s_addc_u32 s1, s7, s10
	global_store_dwordx2 v3, v[14:15], s[0:1]
	s_branch .LBB0_25
